# SSD masked G tile: dt/decay rows read with 8 ds_read_b128 up front, causal mask by v_cndmask (was 16 exec-masked branches with ds_read+lgkmcnt(0) each)
# baseline (speedup 1.0000x reference)
.LBB0_842:
	v_lshlrev_b32_e32 v92, 4, v202
	v_add_u32_e32 v84, s77, v92
	v_mul_lo_u32 v80, v105, s85
	s_waitcnt lgkmcnt(0)
	s_barrier
	v_lshl_add_u32 v123, v202, 4, s5
	v_add_u32_e32 v1, v84, v80
	ds_read_b128 v[72:75], v1 offset:9216
	v_add_u32_e32 v3, s54, v105
	v_mul_lo_u32 v2, v3, s85
	v_add_u32_e32 v89, v84, v2
	v_lshl_add_u32 v2, v3, 2, s5
	ds_read_b128 v[68:71], v89
	ds_read_b128 v[64:67], v89 offset:64
	ds_read_b32 v81, v2 offset:64768
	ds_read_b128 v[76:79], v1 offset:9280
	s_waitcnt lgkmcnt(3)
	v_mfma_f32_16x16x32_bf16 v[72:75], v[72:75], v[68:71], 0
	v_lshlrev_b32_e32 v2, 2, v202
	v_cmp_le_i32_e32 vcc, v2, v3
	s_waitcnt lgkmcnt(0)
	v_mfma_f32_16x16x32_bf16 v[72:75], v[76:79], v[64:67], v[72:75]
	ds_read_b128 v[124:127], v123 offset:64512
	ds_read_b128 v[128:131], v123 offset:64768
	ds_read_b128 v[132:135], v123 offset:64576
	ds_read_b128 v[136:139], v123 offset:64832
	ds_read_b128 v[140:143], v123 offset:64640
	ds_read_b128 v[144:147], v123 offset:64896
	ds_read_b128 v[148:151], v123 offset:64704
	ds_read_b128 v[152:155], v123 offset:64960
	v_cndmask_b32_e64 v76, 0, 1, vcc
	v_cmp_ge_i32_e32 vcc, v2, v3
	v_lshl_add_u32 v78, v2, 2, s5
	s_nop 0
	v_cndmask_b32_e64 v77, 0, 1, vcc
	v_cndmask_b32_e64 v76, v77, v76, s[6:7]
	v_and_b32_e32 v76, 1, v76
	v_cmp_eq_u32_e32 vcc, 1, v76
	v_mov_b32_e32 v77, 0
	v_mov_b32_e32 v76, 0
	s_waitcnt lgkmcnt(6)
	v_sub_f32_e32 v122, v81, v128
	v_mul_f32_e32 v122, 0x3fb8aa3b, v122
	v_exp_f32_e32 v122, v122
	s_nop 0
	v_mul_f32_e32 v122, v72, v122
	v_mul_f32_e32 v122, v124, v122
	v_cndmask_b32_e32 v76, 0, v122, vcc
	v_or_b32_e32 v90, 1, v2
	v_cmp_lt_i32_e32 vcc, v2, v3
	v_mov_b32_e32 v82, 0
	s_nop 0
	v_cndmask_b32_e64 v72, 0, 1, vcc
	v_cmp_ge_i32_e32 vcc, v90, v3
	s_nop 1
	v_cndmask_b32_e64 v79, 0, 1, vcc
	v_cndmask_b32_e64 v72, v79, v72, s[6:7]
	v_and_b32_e32 v72, 1, v72
	v_cmp_eq_u32_e32 vcc, 1, v72
	v_sub_f32_e32 v122, v81, v129
	v_mul_f32_e32 v122, 0x3fb8aa3b, v122
	v_exp_f32_e32 v122, v122
	s_nop 0
	v_mul_f32_e32 v122, v73, v122
	v_mul_f32_e32 v122, v125, v122
	v_cndmask_b32_e32 v82, 0, v122, vcc
	v_or_b32_e32 v91, 2, v2
	v_cmp_le_i32_e32 vcc, v91, v3
	s_nop 1
	v_cndmask_b32_e64 v72, 0, 1, vcc
	v_cmp_ge_i32_e32 vcc, v91, v3
	s_nop 1
	v_cndmask_b32_e64 v73, 0, 1, vcc
	v_cndmask_b32_e64 v72, v73, v72, s[6:7]
	v_and_b32_e32 v72, 1, v72
	v_cmp_eq_u32_e32 vcc, 1, v72
	v_sub_f32_e32 v122, v81, v130
	v_mul_f32_e32 v122, 0x3fb8aa3b, v122
	v_exp_f32_e32 v122, v122
	s_nop 0
	v_mul_f32_e32 v122, v74, v122
	v_mul_f32_e32 v122, v126, v122
	v_cndmask_b32_e32 v77, 0, v122, vcc
	v_or_b32_e32 v113, 3, v2
	v_cmp_le_i32_e32 vcc, v113, v3
	v_mov_b32_e32 v79, 0
	v_mov_b32_e32 v83, 0
	v_cndmask_b32_e64 v72, 0, 1, vcc
	v_cmp_ge_i32_e32 vcc, v113, v3
	s_nop 1
	v_cndmask_b32_e64 v73, 0, 1, vcc
	v_cndmask_b32_e64 v72, v73, v72, s[6:7]
	v_and_b32_e32 v72, 1, v72
	v_cmp_eq_u32_e32 vcc, 1, v72
	v_sub_f32_e32 v122, v81, v131
	v_mul_f32_e32 v122, 0x3fb8aa3b, v122
	v_exp_f32_e32 v122, v122
	s_nop 0
	v_mul_f32_e32 v122, v75, v122
	v_mul_f32_e32 v122, v127, v122
	v_cndmask_b32_e32 v83, 0, v122, vcc
	v_add_u32_e32 v112, 0x900, v80
	v_add_u32_e32 v85, v84, v112
	ds_read_b128 v[72:75], v85 offset:9216
	ds_read_b128 v[94:97], v85 offset:9280
	v_add_u32_e32 v100, 16, v2
	v_cmp_le_i32_e32 vcc, v100, v3
	s_waitcnt lgkmcnt(1)
	v_mfma_f32_16x16x32_bf16 v[72:75], v[72:75], v[68:71], 0
	v_cndmask_b32_e64 v85, 0, 1, vcc
	v_cmp_ge_i32_e32 vcc, v100, v3
	s_waitcnt lgkmcnt(0)
	v_mfma_f32_16x16x32_bf16 v[72:75], v[94:97], v[64:67], v[72:75]
	v_cndmask_b32_e64 v86, 0, 1, vcc
	v_cndmask_b32_e64 v85, v86, v85, s[6:7]
	v_and_b32_e32 v85, 1, v85
	v_cmp_eq_u32_e32 vcc, 1, v85
	s_nop 1
	v_sub_f32_e32 v122, v81, v136
	v_mul_f32_e32 v122, 0x3fb8aa3b, v122
	v_exp_f32_e32 v122, v122
	s_nop 0
	v_mul_f32_e32 v122, v72, v122
	v_mul_f32_e32 v122, v132, v122
	v_cndmask_b32_e32 v79, 0, v122, vcc
	v_add_u32_e32 v103, 17, v2
	v_cmp_le_i32_e32 vcc, v103, v3
	v_mov_b32_e32 v86, 0
	s_nop 0
	v_cndmask_b32_e64 v72, 0, 1, vcc
	v_cmp_ge_i32_e32 vcc, v103, v3
	s_nop 1
	v_cndmask_b32_e64 v85, 0, 1, vcc
	v_cndmask_b32_e64 v72, v85, v72, s[6:7]
	v_and_b32_e32 v72, 1, v72
	v_cmp_eq_u32_e32 vcc, 1, v72
	v_mov_b32_e32 v85, 0
	v_sub_f32_e32 v122, v81, v137
	v_mul_f32_e32 v122, 0x3fb8aa3b, v122
	v_exp_f32_e32 v122, v122
	s_nop 0
	v_mul_f32_e32 v122, v73, v122
	v_mul_f32_e32 v122, v133, v122
	v_cndmask_b32_e32 v86, 0, v122, vcc
	v_add_u32_e32 v109, 18, v2
	v_cmp_le_i32_e32 vcc, v109, v3
	s_nop 1
	v_cndmask_b32_e64 v72, 0, 1, vcc
	v_cmp_ge_i32_e32 vcc, v109, v3
	s_nop 1
	v_cndmask_b32_e64 v73, 0, 1, vcc
	v_cndmask_b32_e64 v72, v73, v72, s[6:7]
	v_and_b32_e32 v72, 1, v72
	v_cmp_eq_u32_e32 vcc, 1, v72
	v_sub_f32_e32 v122, v81, v138
	v_mul_f32_e32 v122, 0x3fb8aa3b, v122
	v_exp_f32_e32 v122, v122
	s_nop 0
	v_mul_f32_e32 v122, v74, v122
	v_mul_f32_e32 v122, v134, v122
	v_cndmask_b32_e32 v85, 0, v122, vcc
	v_add_u32_e32 v111, 19, v2
	v_cmp_le_i32_e32 vcc, v111, v3
	v_mov_b32_e32 v88, 0
	v_mov_b32_e32 v87, 0
	v_cndmask_b32_e64 v72, 0, 1, vcc
	v_cmp_ge_i32_e32 vcc, v111, v3
	s_nop 1
	v_cndmask_b32_e64 v73, 0, 1, vcc
	v_cndmask_b32_e64 v72, v73, v72, s[6:7]
	v_and_b32_e32 v72, 1, v72
	v_cmp_eq_u32_e32 vcc, 1, v72
	v_sub_f32_e32 v122, v81, v139
	v_mul_f32_e32 v122, 0x3fb8aa3b, v122
	v_exp_f32_e32 v122, v122
	s_nop 0
	v_mul_f32_e32 v122, v75, v122
	v_mul_f32_e32 v122, v135, v122
	v_cndmask_b32_e32 v87, 0, v122, vcc
	v_add_u32_e32 v110, 0x900, v112
	v_add_u32_e32 v93, v84, v110
	ds_read_b128 v[72:75], v93 offset:9216
	ds_read_b128 v[114:117], v93 offset:9280
	v_add_u32_e32 v96, 32, v2
	v_cmp_le_i32_e32 vcc, v96, v3
	s_waitcnt lgkmcnt(1)
	v_mfma_f32_16x16x32_bf16 v[72:75], v[72:75], v[68:71], 0
	v_cndmask_b32_e64 v93, 0, 1, vcc
	v_cmp_ge_i32_e32 vcc, v96, v3
	s_waitcnt lgkmcnt(0)
	v_mfma_f32_16x16x32_bf16 v[72:75], v[114:117], v[64:67], v[72:75]
	v_cndmask_b32_e64 v94, 0, 1, vcc
	v_cndmask_b32_e64 v93, v94, v93, s[6:7]
	v_and_b32_e32 v93, 1, v93
	v_cmp_eq_u32_e32 vcc, 1, v93
	s_nop 1
	v_sub_f32_e32 v122, v81, v144
	v_mul_f32_e32 v122, 0x3fb8aa3b, v122
	v_exp_f32_e32 v122, v122
	s_nop 0
	v_mul_f32_e32 v122, v72, v122
	v_mul_f32_e32 v122, v140, v122
	v_cndmask_b32_e32 v88, 0, v122, vcc
	v_add_u32_e32 v98, 33, v2
	v_cmp_le_i32_e32 vcc, v98, v3
	v_mov_b32_e32 v108, 0
	v_mov_b32_e32 v114, 0
	v_cndmask_b32_e64 v72, 0, 1, vcc
	v_cmp_ge_i32_e32 vcc, v98, v3
	s_nop 1
	v_cndmask_b32_e64 v93, 0, 1, vcc
	v_cndmask_b32_e64 v72, v93, v72, s[6:7]
	v_and_b32_e32 v72, 1, v72
	v_cmp_eq_u32_e32 vcc, 1, v72
	v_sub_f32_e32 v122, v81, v145
	v_mul_f32_e32 v122, 0x3fb8aa3b, v122
	v_exp_f32_e32 v122, v122
	s_nop 0
	v_mul_f32_e32 v122, v73, v122
	v_mul_f32_e32 v122, v141, v122
	v_cndmask_b32_e32 v114, 0, v122, vcc
	v_add_u32_e32 v99, 34, v2
	v_cmp_le_i32_e32 vcc, v99, v3
	s_nop 1
	v_cndmask_b32_e64 v72, 0, 1, vcc
	v_cmp_ge_i32_e32 vcc, v99, v3
	s_nop 1
	v_cndmask_b32_e64 v73, 0, 1, vcc
	v_cndmask_b32_e64 v72, v73, v72, s[6:7]
	v_and_b32_e32 v72, 1, v72
	v_cmp_eq_u32_e32 vcc, 1, v72
	v_sub_f32_e32 v122, v81, v146
	v_mul_f32_e32 v122, 0x3fb8aa3b, v122
	v_exp_f32_e32 v122, v122
	s_nop 0
	v_mul_f32_e32 v122, v74, v122
	v_mul_f32_e32 v122, v142, v122
	v_cndmask_b32_e32 v108, 0, v122, vcc
	v_add_u32_e32 v102, 35, v2
	v_cmp_le_i32_e32 vcc, v102, v3
	v_mov_b32_e32 v115, 0
	v_mov_b32_e32 v116, 0
	v_cndmask_b32_e64 v72, 0, 1, vcc
	v_cmp_ge_i32_e32 vcc, v102, v3
	s_nop 1
	v_cndmask_b32_e64 v73, 0, 1, vcc
	v_cndmask_b32_e64 v72, v73, v72, s[6:7]
	v_and_b32_e32 v72, 1, v72
	v_cmp_eq_u32_e32 vcc, 1, v72
	v_sub_f32_e32 v122, v81, v147
	v_mul_f32_e32 v122, 0x3fb8aa3b, v122
	v_exp_f32_e32 v122, v122
	s_nop 0
	v_mul_f32_e32 v122, v75, v122
	v_mul_f32_e32 v122, v143, v122
	v_cndmask_b32_e32 v116, 0, v122, vcc
	v_add_u32_e32 v101, 0x900, v110
	v_add_u32_e32 v84, v84, v101
	ds_read_b128 v[72:75], v84 offset:9216
	ds_read_b128 v[118:121], v84 offset:9280
	v_add_u32_e32 v93, 48, v2
	v_cmp_le_i32_e32 vcc, v93, v3
	s_waitcnt lgkmcnt(1)
	v_mfma_f32_16x16x32_bf16 v[72:75], v[72:75], v[68:71], 0
	v_cndmask_b32_e64 v84, 0, 1, vcc
	v_cmp_ge_i32_e32 vcc, v93, v3
	s_waitcnt lgkmcnt(0)
	v_mfma_f32_16x16x32_bf16 v[72:75], v[118:121], v[64:67], v[72:75]
	v_cndmask_b32_e64 v94, 0, 1, vcc
	v_cndmask_b32_e64 v84, v94, v84, s[6:7]
	v_and_b32_e32 v84, 1, v84
	v_cmp_eq_u32_e32 vcc, 1, v84
	s_nop 1
	v_sub_f32_e32 v122, v81, v152
	v_mul_f32_e32 v122, 0x3fb8aa3b, v122
	v_exp_f32_e32 v122, v122
	s_nop 0
	v_mul_f32_e32 v122, v72, v122
	v_mul_f32_e32 v122, v148, v122
	v_cndmask_b32_e32 v115, 0, v122, vcc
	v_add_u32_e32 v94, 49, v2
	v_cmp_le_i32_e32 vcc, v94, v3
	v_mov_b32_e32 v117, 0
	s_nop 0
	v_cndmask_b32_e64 v72, 0, 1, vcc
	v_cmp_ge_i32_e32 vcc, v94, v3
	s_nop 1
	v_cndmask_b32_e64 v84, 0, 1, vcc
	v_cndmask_b32_e64 v72, v84, v72, s[6:7]
	v_and_b32_e32 v72, 1, v72
	v_cmp_eq_u32_e32 vcc, 1, v72
	v_mov_b32_e32 v84, 0
	v_sub_f32_e32 v122, v81, v153
	v_mul_f32_e32 v122, 0x3fb8aa3b, v122
	v_exp_f32_e32 v122, v122
	s_nop 0
	v_mul_f32_e32 v122, v73, v122
	v_mul_f32_e32 v122, v149, v122
	v_cndmask_b32_e32 v117, 0, v122, vcc
	v_add_u32_e32 v95, 50, v2
	v_cmp_le_i32_e32 vcc, v95, v3
	s_nop 1
	v_cndmask_b32_e64 v72, 0, 1, vcc
	v_cmp_ge_i32_e32 vcc, v95, v3
	s_nop 1
	v_cndmask_b32_e64 v73, 0, 1, vcc
	v_cndmask_b32_e64 v72, v73, v72, s[6:7]
	v_and_b32_e32 v72, 1, v72
	v_cmp_eq_u32_e32 vcc, 1, v72
	v_sub_f32_e32 v122, v81, v154
	v_mul_f32_e32 v122, 0x3fb8aa3b, v122
	v_exp_f32_e32 v122, v122
	s_nop 0
	v_mul_f32_e32 v122, v74, v122
	v_mul_f32_e32 v122, v150, v122
	v_cndmask_b32_e32 v84, 0, v122, vcc
	v_add_u32_e32 v97, 51, v2
	v_cmp_le_i32_e32 vcc, v97, v3
	v_mov_b32_e32 v118, 0
	s_nop 0
	v_cndmask_b32_e64 v72, 0, 1, vcc
	v_cmp_ge_i32_e32 vcc, v97, v3
	s_nop 1
	v_cndmask_b32_e64 v73, 0, 1, vcc
	v_cndmask_b32_e64 v72, v73, v72, s[6:7]
	v_and_b32_e32 v72, 1, v72
	v_cmp_eq_u32_e32 vcc, 1, v72
	v_sub_f32_e32 v122, v81, v155
	v_mul_f32_e32 v122, 0x3fb8aa3b, v122
	v_exp_f32_e32 v122, v122
	s_nop 0
	v_mul_f32_e32 v122, v75, v122
	v_mul_f32_e32 v122, v151, v122
	v_cndmask_b32_e32 v118, 0, v122, vcc
	v_cvt_pk_bf16_f32 v76, v76, v82
	v_cvt_pk_bf16_f32 v75, v84, v118
	v_lshlrev_b32_e32 v82, 1, v105
	v_and_b32_e32 v84, 3, v105
	v_cvt_pk_bf16_f32 v77, v77, v83
	v_mul_f32_e32 v81, 0x3fb8aa3b, v81
	v_lshrrev_b32_e32 v83, 2, v3
	v_and_or_b32 v82, v82, 24, v84
	v_add_u32_e32 v84, v80, v92
	v_cvt_pk_bf16_f32 v72, v88, v114
	v_cvt_pk_bf16_f32 v73, v108, v116
	v_exp_f32_e32 v108, v81
	v_and_b32_e32 v81, 32, v3
	v_and_b32_e32 v83, 4, v83
	v_add_u32_e32 v114, s77, v84
	v_or3_b32 v88, v82, v81, v83
	ds_read_b128 v[80:83], v114 offset:27648
	s_mul_i32 s5, s51, 0x2400
	s_add_i32 s5, s77, s5
	v_add_u32_e32 v118, s5, v84
	v_cvt_pk_bf16_f32 v78, v79, v86
	v_cvt_pk_bf16_f32 v79, v85, v87
	v_cvt_pk_bf16_f32 v74, v115, v117
	ds_read_b128 v[84:87], v118 offset:46080
	ds_read_b128 v[114:117], v114 offset:27712
	s_waitcnt lgkmcnt(2)
	v_mfma_f32_16x16x32_bf16 v[80:83], v[80:83], v[76:79], 0
	s_andn2_b64 vcc, exec, s[6:7]
	s_waitcnt lgkmcnt(0)
	v_mfma_f32_16x16x32_bf16 v[80:83], v[114:117], v[72:75], v[80:83]
	ds_read_b128 v[114:117], v118 offset:46144
	v_mfma_f32_16x16x32_bf16 v[84:87], v[84:87], v[68:71], 0
	s_waitcnt lgkmcnt(0)
	v_mfma_f32_16x16x32_bf16 v[84:87], v[114:117], v[64:67], v[84:87]
	s_nop 7
	v_fma_f32 v80, v108, v84, v80
	v_cndmask_b32_e64 v84, 0, 1, s[6:7]
	v_cmp_ne_u32_e64 s[10:11], 1, v84
	s_cbranch_vccz .LBB0_901
	s_and_b64 vcc, exec, s[10:11]
	v_fma_f32 v81, v108, v85, v81
	s_cbranch_vccz .LBB0_902

.LBB0_1021:
	v_lshlrev_b32_e32 v92, 4, v200
	v_add_u32_e32 v84, s51, v92
	v_mul_lo_u32 v80, v189, s85
	s_waitcnt lgkmcnt(0)
	s_barrier
	v_lshl_add_u32 v123, v200, 4, s5
	v_add_u32_e32 v1, v84, v80
	ds_read_b128 v[72:75], v1 offset:9216
	v_add_u32_e32 v3, s49, v189
	v_mul_lo_u32 v2, v3, s85
	v_add_u32_e32 v89, v84, v2
	v_lshl_add_u32 v2, v3, 2, s5
	ds_read_b128 v[68:71], v89
	ds_read_b128 v[64:67], v89 offset:64
	ds_read_b32 v81, v2 offset:64768
	ds_read_b128 v[76:79], v1 offset:9280
	s_waitcnt lgkmcnt(3)
	v_mfma_f32_16x16x32_bf16 v[72:75], v[72:75], v[68:71], 0
	v_lshlrev_b32_e32 v2, 2, v200
	v_cmp_le_i32_e32 vcc, v2, v3
	s_waitcnt lgkmcnt(0)
	v_mfma_f32_16x16x32_bf16 v[72:75], v[76:79], v[64:67], v[72:75]
	ds_read_b128 v[124:127], v123 offset:64512
	ds_read_b128 v[128:131], v123 offset:64768
	ds_read_b128 v[132:135], v123 offset:64576
	ds_read_b128 v[136:139], v123 offset:64832
	ds_read_b128 v[140:143], v123 offset:64640
	ds_read_b128 v[144:147], v123 offset:64896
	ds_read_b128 v[148:151], v123 offset:64704
	ds_read_b128 v[152:155], v123 offset:64960
	v_cndmask_b32_e64 v76, 0, 1, vcc
	v_cmp_ge_i32_e32 vcc, v2, v3
	v_lshl_add_u32 v78, v2, 2, s5
	s_nop 0
	v_cndmask_b32_e64 v77, 0, 1, vcc
	v_cndmask_b32_e64 v76, v77, v76, s[6:7]
	v_and_b32_e32 v76, 1, v76
	v_cmp_eq_u32_e32 vcc, 1, v76
	v_mov_b32_e32 v77, 0
	v_mov_b32_e32 v76, 0
	s_waitcnt lgkmcnt(6)
	v_sub_f32_e32 v122, v81, v128
	v_mul_f32_e32 v122, 0x3fb8aa3b, v122
	v_exp_f32_e32 v122, v122
	s_nop 0
	v_mul_f32_e32 v122, v72, v122
	v_mul_f32_e32 v122, v124, v122
	v_cndmask_b32_e32 v76, 0, v122, vcc
	v_or_b32_e32 v90, 1, v2
	v_cmp_lt_i32_e32 vcc, v2, v3
	v_mov_b32_e32 v82, 0
	s_nop 0
	v_cndmask_b32_e64 v72, 0, 1, vcc
	v_cmp_ge_i32_e32 vcc, v90, v3
	s_nop 1
	v_cndmask_b32_e64 v79, 0, 1, vcc
	v_cndmask_b32_e64 v72, v79, v72, s[6:7]
	v_and_b32_e32 v72, 1, v72
	v_cmp_eq_u32_e32 vcc, 1, v72
	v_sub_f32_e32 v122, v81, v129
	v_mul_f32_e32 v122, 0x3fb8aa3b, v122
	v_exp_f32_e32 v122, v122
	s_nop 0
	v_mul_f32_e32 v122, v73, v122
	v_mul_f32_e32 v122, v125, v122
	v_cndmask_b32_e32 v82, 0, v122, vcc
	v_or_b32_e32 v91, 2, v2
	v_cmp_le_i32_e32 vcc, v91, v3
	s_nop 1
	v_cndmask_b32_e64 v72, 0, 1, vcc
	v_cmp_ge_i32_e32 vcc, v91, v3
	s_nop 1
	v_cndmask_b32_e64 v73, 0, 1, vcc
	v_cndmask_b32_e64 v72, v73, v72, s[6:7]
	v_and_b32_e32 v72, 1, v72
	v_cmp_eq_u32_e32 vcc, 1, v72
	v_sub_f32_e32 v122, v81, v130
	v_mul_f32_e32 v122, 0x3fb8aa3b, v122
	v_exp_f32_e32 v122, v122
	s_nop 0
	v_mul_f32_e32 v122, v74, v122
	v_mul_f32_e32 v122, v126, v122
	v_cndmask_b32_e32 v77, 0, v122, vcc
	v_or_b32_e32 v113, 3, v2
	v_cmp_le_i32_e32 vcc, v113, v3
	v_mov_b32_e32 v79, 0
	v_mov_b32_e32 v83, 0
	v_cndmask_b32_e64 v72, 0, 1, vcc
	v_cmp_ge_i32_e32 vcc, v113, v3
	s_nop 1
	v_cndmask_b32_e64 v73, 0, 1, vcc
	v_cndmask_b32_e64 v72, v73, v72, s[6:7]
	v_and_b32_e32 v72, 1, v72
	v_cmp_eq_u32_e32 vcc, 1, v72
	v_sub_f32_e32 v122, v81, v131
	v_mul_f32_e32 v122, 0x3fb8aa3b, v122
	v_exp_f32_e32 v122, v122
	s_nop 0
	v_mul_f32_e32 v122, v75, v122
	v_mul_f32_e32 v122, v127, v122
	v_cndmask_b32_e32 v83, 0, v122, vcc
	v_add_u32_e32 v112, 0x900, v80
	v_add_u32_e32 v85, v84, v112
	ds_read_b128 v[72:75], v85 offset:9216
	ds_read_b128 v[94:97], v85 offset:9280
	v_add_u32_e32 v100, 16, v2
	v_cmp_le_i32_e32 vcc, v100, v3
	s_waitcnt lgkmcnt(1)
	v_mfma_f32_16x16x32_bf16 v[72:75], v[72:75], v[68:71], 0
	v_cndmask_b32_e64 v85, 0, 1, vcc
	v_cmp_ge_i32_e32 vcc, v100, v3
	s_waitcnt lgkmcnt(0)
	v_mfma_f32_16x16x32_bf16 v[72:75], v[94:97], v[64:67], v[72:75]
	v_cndmask_b32_e64 v86, 0, 1, vcc
	v_cndmask_b32_e64 v85, v86, v85, s[6:7]
	v_and_b32_e32 v85, 1, v85
	v_cmp_eq_u32_e32 vcc, 1, v85
	s_nop 1
	v_sub_f32_e32 v122, v81, v136
	v_mul_f32_e32 v122, 0x3fb8aa3b, v122
	v_exp_f32_e32 v122, v122
	s_nop 0
	v_mul_f32_e32 v122, v72, v122
	v_mul_f32_e32 v122, v132, v122
	v_cndmask_b32_e32 v79, 0, v122, vcc
	v_add_u32_e32 v103, 17, v2
	v_cmp_le_i32_e32 vcc, v103, v3
	v_mov_b32_e32 v86, 0
	s_nop 0
	v_cndmask_b32_e64 v72, 0, 1, vcc
	v_cmp_ge_i32_e32 vcc, v103, v3
	s_nop 1
	v_cndmask_b32_e64 v85, 0, 1, vcc
	v_cndmask_b32_e64 v72, v85, v72, s[6:7]
	v_and_b32_e32 v72, 1, v72
	v_cmp_eq_u32_e32 vcc, 1, v72
	v_mov_b32_e32 v85, 0
	v_sub_f32_e32 v122, v81, v137
	v_mul_f32_e32 v122, 0x3fb8aa3b, v122
	v_exp_f32_e32 v122, v122
	s_nop 0
	v_mul_f32_e32 v122, v73, v122
	v_mul_f32_e32 v122, v133, v122
	v_cndmask_b32_e32 v86, 0, v122, vcc
	v_add_u32_e32 v109, 18, v2
	v_cmp_le_i32_e32 vcc, v109, v3
	s_nop 1
	v_cndmask_b32_e64 v72, 0, 1, vcc
	v_cmp_ge_i32_e32 vcc, v109, v3
	s_nop 1
	v_cndmask_b32_e64 v73, 0, 1, vcc
	v_cndmask_b32_e64 v72, v73, v72, s[6:7]
	v_and_b32_e32 v72, 1, v72
	v_cmp_eq_u32_e32 vcc, 1, v72
	v_sub_f32_e32 v122, v81, v138
	v_mul_f32_e32 v122, 0x3fb8aa3b, v122
	v_exp_f32_e32 v122, v122
	s_nop 0
	v_mul_f32_e32 v122, v74, v122
	v_mul_f32_e32 v122, v134, v122
	v_cndmask_b32_e32 v85, 0, v122, vcc
	v_add_u32_e32 v111, 19, v2
	v_cmp_le_i32_e32 vcc, v111, v3
	v_mov_b32_e32 v88, 0
	v_mov_b32_e32 v87, 0
	v_cndmask_b32_e64 v72, 0, 1, vcc
	v_cmp_ge_i32_e32 vcc, v111, v3
	s_nop 1
	v_cndmask_b32_e64 v73, 0, 1, vcc
	v_cndmask_b32_e64 v72, v73, v72, s[6:7]
	v_and_b32_e32 v72, 1, v72
	v_cmp_eq_u32_e32 vcc, 1, v72
	v_sub_f32_e32 v122, v81, v139
	v_mul_f32_e32 v122, 0x3fb8aa3b, v122
	v_exp_f32_e32 v122, v122
	s_nop 0
	v_mul_f32_e32 v122, v75, v122
	v_mul_f32_e32 v122, v135, v122
	v_cndmask_b32_e32 v87, 0, v122, vcc
	v_add_u32_e32 v110, 0x900, v112
	v_add_u32_e32 v93, v84, v110
	ds_read_b128 v[72:75], v93 offset:9216
	ds_read_b128 v[114:117], v93 offset:9280
	v_add_u32_e32 v96, 32, v2
	v_cmp_le_i32_e32 vcc, v96, v3
	s_waitcnt lgkmcnt(1)
	v_mfma_f32_16x16x32_bf16 v[72:75], v[72:75], v[68:71], 0
	v_cndmask_b32_e64 v93, 0, 1, vcc
	v_cmp_ge_i32_e32 vcc, v96, v3
	s_waitcnt lgkmcnt(0)
	v_mfma_f32_16x16x32_bf16 v[72:75], v[114:117], v[64:67], v[72:75]
	v_cndmask_b32_e64 v94, 0, 1, vcc
	v_cndmask_b32_e64 v93, v94, v93, s[6:7]
	v_and_b32_e32 v93, 1, v93
	v_cmp_eq_u32_e32 vcc, 1, v93
	s_nop 1
	v_sub_f32_e32 v122, v81, v144
	v_mul_f32_e32 v122, 0x3fb8aa3b, v122
	v_exp_f32_e32 v122, v122
	s_nop 0
	v_mul_f32_e32 v122, v72, v122
	v_mul_f32_e32 v122, v140, v122
	v_cndmask_b32_e32 v88, 0, v122, vcc
	v_add_u32_e32 v98, 33, v2
	v_cmp_le_i32_e32 vcc, v98, v3
	v_mov_b32_e32 v108, 0
	v_mov_b32_e32 v114, 0
	v_cndmask_b32_e64 v72, 0, 1, vcc
	v_cmp_ge_i32_e32 vcc, v98, v3
	s_nop 1
	v_cndmask_b32_e64 v93, 0, 1, vcc
	v_cndmask_b32_e64 v72, v93, v72, s[6:7]
	v_and_b32_e32 v72, 1, v72
	v_cmp_eq_u32_e32 vcc, 1, v72
	v_sub_f32_e32 v122, v81, v145
	v_mul_f32_e32 v122, 0x3fb8aa3b, v122
	v_exp_f32_e32 v122, v122
	s_nop 0
	v_mul_f32_e32 v122, v73, v122
	v_mul_f32_e32 v122, v141, v122
	v_cndmask_b32_e32 v114, 0, v122, vcc
	v_add_u32_e32 v99, 34, v2
	v_cmp_le_i32_e32 vcc, v99, v3
	s_nop 1
	v_cndmask_b32_e64 v72, 0, 1, vcc
	v_cmp_ge_i32_e32 vcc, v99, v3
	s_nop 1
	v_cndmask_b32_e64 v73, 0, 1, vcc
	v_cndmask_b32_e64 v72, v73, v72, s[6:7]
	v_and_b32_e32 v72, 1, v72
	v_cmp_eq_u32_e32 vcc, 1, v72
	v_sub_f32_e32 v122, v81, v146
	v_mul_f32_e32 v122, 0x3fb8aa3b, v122
	v_exp_f32_e32 v122, v122
	s_nop 0
	v_mul_f32_e32 v122, v74, v122
	v_mul_f32_e32 v122, v142, v122
	v_cndmask_b32_e32 v108, 0, v122, vcc
	v_add_u32_e32 v102, 35, v2
	v_cmp_le_i32_e32 vcc, v102, v3
	v_mov_b32_e32 v115, 0
	v_mov_b32_e32 v116, 0
	v_cndmask_b32_e64 v72, 0, 1, vcc
	v_cmp_ge_i32_e32 vcc, v102, v3
	s_nop 1
	v_cndmask_b32_e64 v73, 0, 1, vcc
	v_cndmask_b32_e64 v72, v73, v72, s[6:7]
	v_and_b32_e32 v72, 1, v72
	v_cmp_eq_u32_e32 vcc, 1, v72
	v_sub_f32_e32 v122, v81, v147
	v_mul_f32_e32 v122, 0x3fb8aa3b, v122
	v_exp_f32_e32 v122, v122
	s_nop 0
	v_mul_f32_e32 v122, v75, v122
	v_mul_f32_e32 v122, v143, v122
	v_cndmask_b32_e32 v116, 0, v122, vcc
	v_add_u32_e32 v101, 0x900, v110
	v_add_u32_e32 v84, v84, v101
	ds_read_b128 v[72:75], v84 offset:9216
	ds_read_b128 v[118:121], v84 offset:9280
	v_add_u32_e32 v93, 48, v2
	v_cmp_le_i32_e32 vcc, v93, v3
	s_waitcnt lgkmcnt(1)
	v_mfma_f32_16x16x32_bf16 v[72:75], v[72:75], v[68:71], 0
	v_cndmask_b32_e64 v84, 0, 1, vcc
	v_cmp_ge_i32_e32 vcc, v93, v3
	s_waitcnt lgkmcnt(0)
	v_mfma_f32_16x16x32_bf16 v[72:75], v[118:121], v[64:67], v[72:75]
	v_cndmask_b32_e64 v94, 0, 1, vcc
	v_cndmask_b32_e64 v84, v94, v84, s[6:7]
	v_and_b32_e32 v84, 1, v84
	v_cmp_eq_u32_e32 vcc, 1, v84
	s_nop 1
	v_sub_f32_e32 v122, v81, v152
	v_mul_f32_e32 v122, 0x3fb8aa3b, v122
	v_exp_f32_e32 v122, v122
	s_nop 0
	v_mul_f32_e32 v122, v72, v122
	v_mul_f32_e32 v122, v148, v122
	v_cndmask_b32_e32 v115, 0, v122, vcc
	v_add_u32_e32 v94, 49, v2
	v_cmp_le_i32_e32 vcc, v94, v3
	v_mov_b32_e32 v117, 0
	s_nop 0
	v_cndmask_b32_e64 v72, 0, 1, vcc
	v_cmp_ge_i32_e32 vcc, v94, v3
	s_nop 1
	v_cndmask_b32_e64 v84, 0, 1, vcc
	v_cndmask_b32_e64 v72, v84, v72, s[6:7]
	v_and_b32_e32 v72, 1, v72
	v_cmp_eq_u32_e32 vcc, 1, v72
	v_mov_b32_e32 v84, 0
	v_sub_f32_e32 v122, v81, v153
	v_mul_f32_e32 v122, 0x3fb8aa3b, v122
	v_exp_f32_e32 v122, v122
	s_nop 0
	v_mul_f32_e32 v122, v73, v122
	v_mul_f32_e32 v122, v149, v122
	v_cndmask_b32_e32 v117, 0, v122, vcc
	v_add_u32_e32 v95, 50, v2
	v_cmp_le_i32_e32 vcc, v95, v3
	s_nop 1
	v_cndmask_b32_e64 v72, 0, 1, vcc
	v_cmp_ge_i32_e32 vcc, v95, v3
	s_nop 1
	v_cndmask_b32_e64 v73, 0, 1, vcc
	v_cndmask_b32_e64 v72, v73, v72, s[6:7]
	v_and_b32_e32 v72, 1, v72
	v_cmp_eq_u32_e32 vcc, 1, v72
	v_sub_f32_e32 v122, v81, v154
	v_mul_f32_e32 v122, 0x3fb8aa3b, v122
	v_exp_f32_e32 v122, v122
	s_nop 0
	v_mul_f32_e32 v122, v74, v122
	v_mul_f32_e32 v122, v150, v122
	v_cndmask_b32_e32 v84, 0, v122, vcc
	v_add_u32_e32 v97, 51, v2
	v_cmp_le_i32_e32 vcc, v97, v3
	v_mov_b32_e32 v118, 0
	s_nop 0
	v_cndmask_b32_e64 v72, 0, 1, vcc
	v_cmp_ge_i32_e32 vcc, v97, v3
	s_nop 1
	v_cndmask_b32_e64 v73, 0, 1, vcc
	v_cndmask_b32_e64 v72, v73, v72, s[6:7]
	v_and_b32_e32 v72, 1, v72
	v_cmp_eq_u32_e32 vcc, 1, v72
	v_sub_f32_e32 v122, v81, v155
	v_mul_f32_e32 v122, 0x3fb8aa3b, v122
	v_exp_f32_e32 v122, v122
	s_nop 0
	v_mul_f32_e32 v122, v75, v122
	v_mul_f32_e32 v122, v151, v122
	v_cndmask_b32_e32 v118, 0, v122, vcc
	v_cvt_pk_bf16_f32 v76, v76, v82
	v_cvt_pk_bf16_f32 v75, v84, v118
	v_lshlrev_b32_e32 v82, 1, v189
	v_and_b32_e32 v84, 3, v189
	v_cvt_pk_bf16_f32 v77, v77, v83
	v_mul_f32_e32 v81, 0x3fb8aa3b, v81
	v_lshrrev_b32_e32 v83, 2, v3
	v_and_or_b32 v82, v82, 24, v84
	v_add_u32_e32 v84, v80, v92
	v_cvt_pk_bf16_f32 v72, v88, v114
	v_cvt_pk_bf16_f32 v73, v108, v116
	v_exp_f32_e32 v108, v81
	v_and_b32_e32 v81, 32, v3
	v_and_b32_e32 v83, 4, v83
	v_add_u32_e32 v114, s51, v84
	v_or3_b32 v88, v82, v81, v83
	ds_read_b128 v[80:83], v114 offset:27648
	s_mul_i32 s5, s52, 0x2400
	s_add_i32 s5, s51, s5
	v_add_u32_e32 v118, s5, v84
	v_cvt_pk_bf16_f32 v78, v79, v86
	v_cvt_pk_bf16_f32 v79, v85, v87
	v_cvt_pk_bf16_f32 v74, v115, v117
	ds_read_b128 v[84:87], v118 offset:46080
	ds_read_b128 v[114:117], v114 offset:27712
	s_waitcnt lgkmcnt(2)
	v_mfma_f32_16x16x32_bf16 v[80:83], v[80:83], v[76:79], 0
	s_andn2_b64 vcc, exec, s[6:7]
	s_waitcnt lgkmcnt(0)
	v_mfma_f32_16x16x32_bf16 v[80:83], v[114:117], v[72:75], v[80:83]
	ds_read_b128 v[114:117], v118 offset:46144
	v_mfma_f32_16x16x32_bf16 v[84:87], v[84:87], v[68:71], 0
	s_waitcnt lgkmcnt(0)
	v_mfma_f32_16x16x32_bf16 v[84:87], v[114:117], v[64:67], v[84:87]
	s_nop 7
	v_fma_f32 v80, v108, v84, v80
	v_cndmask_b32_e64 v84, 0, 1, s[6:7]
	v_cmp_ne_u32_e64 s[10:11], 1, v84
	s_cbranch_vccz .LBB0_1078
	s_and_b64 vcc, exec, s[10:11]
	v_fma_f32 v81, v108, v85, v81
	s_cbranch_vccz .LBB0_1079
